# p11pos: NSA compression positional tables staged in LDS once per workgroup (ds_read_b128 instead of 16 global loads per 8 k-steps)
# speedup vs baseline: 1.0077x; 1.0077x over previous
.LBB0_899:
	s_cmp_lt_i32 s94, 12
	s_cselect_b64 s[6:7], -1, 0
	s_and_b64 s[0:1], s[6:7], s[0:1]
	s_andn2_b64 vcc, exec, s[0:1]
	v_lshrrev_b32_e32 v68, 4, v128
	s_cbranch_vccnz .LBB0_915
	v_lshlrev_b32_e32 v0, 4, v129
	global_load_dwordx4 v[2:5], v0, s[72:73]
	global_load_dwordx4 v[6:9], v0, s[74:75]
	v_add_u32_e32 v1, 0x4000, v0
	s_waitcnt vmcnt(0)
	ds_write_b128 v1, v[2:5]
	ds_write_b128 v1, v[6:9] offset:8192
	s_waitcnt lgkmcnt(0)
	s_barrier
	v_and_b32_e32 v0, 48, v158
	s_waitcnt lgkmcnt(0)
	v_mul_u32_u24_e32 v1, 0x90, v0
	v_and_b32_e32 v0, 48, v131
	v_mul_u32_u24_e32 v4, 0x90, v130
	v_lshlrev_b32_e32 v2, 3, v68
	v_add3_u32 v1, 0, v1, v4
	v_lshlrev_b32_e32 v4, 1, v0
	v_lshlrev_b32_e32 v16, 2, v68
	v_and_b32_e32 v6, 48, v128
	s_add_u32 s4, s92, 0x3600000
	v_or_b32_e32 v3, v0, v130
	v_add3_u32 v32, v1, v4, v2
	v_add_u32_e32 v33, v1, v6
	v_or_b32_e32 v1, v16, v0
	s_addc_u32 s5, s93, 0
	v_mov_b32_e32 v5, 0
	v_lshlrev_b32_e32 v14, 9, v1
	v_lshlrev_b32_e32 v4, 7, v3
	v_lshlrev_b32_e32 v1, 10, v129
	v_lshlrev_b32_e32 v3, 12, v130
	s_mov_b32 s0, 0x30000
	s_add_u32 s8, s92, 0x3680000
	v_lshl_add_u64 v[8:9], s[92:93], 0, v[4:5]
	v_mov_b32_e32 v7, v5
	v_and_or_b32 v4, v1, s0, v3
	s_addc_u32 s9, s93, 0
	s_mov_b32 s11, 0
	s_ashr_i32 s3, s96, 2
	s_ashr_i32 s24, s33, 2
	v_lshl_add_u64 v[6:7], v[8:9], 0, v[6:7]
	v_and_b32_e32 v8, 48, v129
	v_mov_b32_e32 v9, v5
	v_lshl_add_u64 v[10:11], s[92:93], 0, v[4:5]
	s_mov_b32 s25, 0x80402011
	s_movk_i32 s26, 0x800
	s_mov_b32 s27, 0x3100000
	v_lshlrev_b32_e32 v12, 2, v2
	v_mov_b32_e32 v13, v5
	s_mov_b32 s28, 0x4001000
	s_mov_b32 s29, 0x4002000
	s_mov_b32 s30, 0x4003000
	s_mov_b64 s[12:13], 0x4000
	s_mov_b64 s[14:15], 0x200
	s_movk_i32 s31, 0xff8
	s_mov_b32 s34, 0x3180000
	v_lshlrev_b32_e32 v14, 1, v14
	v_lshlrev_b32_e32 v4, 1, v0
	v_lshlrev_b32_e32 v16, 1, v16
	s_mov_b32 s35, 0
	s_branch .LBB0_902

.LBB0_902:
	s_add_i32 s10, s35, s3
	s_cmpk_lt_i32 s10, 0x200
	s_cselect_b64 s[16:17], -1, 0
	s_and_b64 s[0:1], s[16:17], exec
	s_cselect_b32 s0, s10, 0x1ff
	s_lshl_b32 s10, s0, 3
	v_and_or_b32 v17, s10, -16, v130
	v_min_i32_e32 v0, 0xff7, v17
	v_mul_hi_i32 v1, v0, s25
	v_add_u32_e32 v1, v1, v0
	v_lshrrev_b32_e32 v2, 31, v1
	v_ashrrev_i32_e32 v1, 9, v1
	v_add_u32_e32 v15, v1, v2
	s_and_b32 s1, s0, 1
	v_mul_i32_i24_e32 v1, 0x3fe, v15
	v_sub_u32_e32 v2, v0, v1
	s_cmp_eq_u32 s1, 0
	v_ashrrev_i32_e32 v18, 1, v2
	v_lshlrev_b32_e32 v0, 13, v15
	s_cselect_b64 s[20:21], -1, 0
	s_bitcmp1_b32 s0, 0
	v_lshl_add_u32 v0, v18, 4, v0
	s_cselect_b64 s[18:19], -1, 0
	s_and_b64 s[0:1], s[20:21], exec
	v_ashrrev_i32_e32 v1, 31, v0
	s_cselect_b32 s22, s26, 0x900
	s_cselect_b32 s1, s73, s75
	s_cselect_b32 s0, s72, s74
	s_cselect_b32 s36, 0, 0x2000
	v_lshlrev_b64 v[0:1], 12, v[0:1]
	s_cselect_b32 s10, s27, 0x3140000
	v_lshl_add_u64 v[20:21], s[0:1], 0, v[12:13]
	v_and_b32_e32 v19, 1, v2
	s_add_u32 s0, s92, s22
	v_lshl_or_b32 v0, v19, 7, v0
	s_addc_u32 s1, s93, 0
	v_lshl_add_u64 v[22:23], s[0:1], 0, v[0:1]
	v_lshl_add_u64 v[24:25], v[10:11], 0, s[10:11]
	s_mov_b64 s[22:23], 0
	v_mov_b32_e32 v0, 0
	v_mov_b32_e32 v1, v5
	v_mov_b32_e32 v2, v5
	v_mov_b32_e32 v3, v5
.LBB0_903:
	v_lshl_add_u64 v[26:27], v[22:23], 0, v[8:9]
	v_add_co_u32_e64 v126, s[0:1], s28, v26
	s_add_i32 s37, s36, s22
	s_addk_i32 s37, 0x4000
	v_add_u32_e32 v200, s37, v12
	s_nop 0
	v_addc_co_u32_e64 v127, s[0:1], 0, v27, s[0:1]
	v_add_co_u32_e64 v148, s[0:1], s29, v26
	v_lshl_add_u64 v[30:31], v[24:25], 0, v[8:9]
	s_nop 0
	v_addc_co_u32_e64 v149, s[0:1], 0, v27, s[0:1]
	v_add_co_u32_e64 v156, s[0:1], s30, v26
	v_add_co_u32_e32 v66, vcc, 0x4000000, v26
	s_nop 0
	v_addc_co_u32_e64 v157, s[0:1], 0, v27, s[0:1]
	ds_read_b128 v[34:37], v200 offset:16
	ds_read_b128 v[38:41], v200
	ds_read_b128 v[42:45], v200 offset:144
	ds_read_b128 v[46:49], v200 offset:128
	global_load_dwordx4 v[50:53], v[30:31], off
	global_load_dwordx4 v[54:57], v[30:31], off offset:64
	ds_read_b128 v[58:61], v200 offset:272
	ds_read_b128 v[62:65], v200 offset:256
	ds_read_b128 v[70:73], v200 offset:400
	ds_read_b128 v[74:77], v200 offset:384
	global_load_dwordx4 v[78:81], v[30:31], off offset:128
	global_load_dwordx4 v[82:85], v[30:31], off offset:192
	ds_read_b128 v[86:89], v200 offset:528
	ds_read_b128 v[90:93], v200 offset:512
	ds_read_b128 v[94:97], v200 offset:656
	ds_read_b128 v[98:101], v200 offset:640
	global_load_dwordx4 v[102:105], v[30:31], off offset:256
	global_load_dwordx4 v[106:109], v[30:31], off offset:320
	ds_read_b128 v[110:113], v200 offset:784
	ds_read_b128 v[114:117], v200 offset:768
	ds_read_b128 v[118:121], v200 offset:912
	ds_read_b128 v[122:125], v200 offset:896
	global_load_dwordx4 v[132:135], v[30:31], off offset:384
	s_nop 0
	global_load_dwordx4 v[28:31], v[30:31], off offset:448
	s_nop 0
	global_load_dwordx4 v[136:139], v[148:149], off offset:-4096
	global_load_dwordx4 v[140:143], v[126:127], off offset:64
	global_load_dwordx4 v[144:147], v[148:149], off
	s_nop 0
	global_load_dwordx4 v[148:151], v[148:149], off offset:64
	s_nop 0
	global_load_dwordx4 v[152:155], v[156:157], off
	s_nop 0
	global_load_dwordx4 v[156:159], v[156:157], off offset:64
	v_addc_co_u32_e32 v67, vcc, 0, v27, vcc
	global_load_dwordx4 v[160:163], v[66:67], off
	global_load_dwordx4 v[164:167], v[66:67], off offset:64
	s_add_u32 s22, s22, 0x400
	s_addc_u32 s23, s23, 0
	v_lshl_add_u64 v[22:23], v[22:23], 0, s[12:13]
	s_cmpk_eq_i32 s22, 0x2000
	v_lshl_add_u64 v[24:25], v[24:25], 0, s[14:15]
	s_waitcnt vmcnt(0) lgkmcnt(0)
	v_lshlrev_b32_e32 v26, 16, v136
	v_and_b32_e32 v27, 0xffff0000, v136
	v_lshlrev_b32_e32 v66, 16, v137
	v_and_b32_e32 v67, 0xffff0000, v137
	v_lshlrev_b32_e32 v126, 16, v138
	v_and_b32_e32 v127, 0xffff0000, v138
	v_lshlrev_b32_e32 v136, 16, v139
	v_and_b32_e32 v137, 0xffff0000, v139
	v_lshlrev_b32_e32 v138, 16, v140
	v_and_b32_e32 v139, 0xffff0000, v140
	v_lshlrev_b32_e32 v140, 16, v141
	v_and_b32_e32 v141, 0xffff0000, v141
	v_lshlrev_b32_e32 v170, 16, v144
	v_and_b32_e32 v171, 0xffff0000, v144
	v_lshlrev_b32_e32 v144, 16, v145
	v_and_b32_e32 v145, 0xffff0000, v145
	v_lshlrev_b32_e32 v174, 16, v148
	v_and_b32_e32 v175, 0xffff0000, v148
	v_lshlrev_b32_e32 v148, 16, v149
	v_and_b32_e32 v149, 0xffff0000, v149
	v_lshlrev_b32_e32 v178, 16, v152
	v_and_b32_e32 v179, 0xffff0000, v152
	v_lshlrev_b32_e32 v152, 16, v153
	v_and_b32_e32 v153, 0xffff0000, v153
	v_lshlrev_b32_e32 v182, 16, v156
	v_and_b32_e32 v183, 0xffff0000, v156
	v_lshlrev_b32_e32 v156, 16, v157
	v_and_b32_e32 v157, 0xffff0000, v157
	v_lshlrev_b32_e32 v186, 16, v160
	v_and_b32_e32 v187, 0xffff0000, v160
	v_lshlrev_b32_e32 v160, 16, v161
	v_and_b32_e32 v161, 0xffff0000, v161
	v_lshlrev_b32_e32 v188, 16, v162
	v_and_b32_e32 v189, 0xffff0000, v162
	v_lshlrev_b32_e32 v162, 16, v163
	v_and_b32_e32 v163, 0xffff0000, v163
	v_lshlrev_b32_e32 v192, 16, v166
	v_and_b32_e32 v193, 0xffff0000, v166
	v_pk_add_f32 v[26:27], v[62:63], v[26:27]
	v_pk_add_f32 v[62:63], v[64:65], v[66:67]
	v_pk_add_f32 v[58:59], v[58:59], v[126:127]
	v_pk_add_f32 v[60:61], v[60:61], v[136:137]
	v_pk_add_f32 v[64:65], v[74:75], v[138:139]
	v_pk_add_f32 v[66:67], v[76:77], v[140:141]
	v_pk_add_f32 v[74:75], v[90:91], v[170:171]
	v_pk_add_f32 v[76:77], v[92:93], v[144:145]
	v_pk_add_f32 v[90:91], v[98:99], v[174:175]
	v_pk_add_f32 v[92:93], v[100:101], v[148:149]
	v_pk_add_f32 v[98:99], v[114:115], v[178:179]
	v_pk_add_f32 v[100:101], v[116:117], v[152:153]
	v_pk_add_f32 v[114:115], v[122:123], v[182:183]
	v_pk_add_f32 v[116:117], v[124:125], v[156:157]
	v_pk_add_f32 v[122:123], v[38:39], v[186:187]
	v_pk_add_f32 v[124:125], v[40:41], v[160:161]
	v_pk_add_f32 v[126:127], v[34:35], v[188:189]
	v_pk_add_f32 v[136:137], v[36:37], v[162:163]
	v_pk_add_f32 v[138:139], v[42:43], v[192:193]
	v_cvt_pk_bf16_f32 v40, v122, v123
	v_cvt_pk_bf16_f32 v41, v124, v125
	v_cvt_pk_bf16_f32 v42, v126, v127
	v_cvt_pk_bf16_f32 v43, v136, v137
	v_lshlrev_b32_e32 v190, 16, v164
	v_and_b32_e32 v191, 0xffff0000, v164
	v_mfma_f32_16x16x32_bf16 v[0:3], v[50:53], v[40:43], v[0:3]
	v_lshlrev_b32_e32 v164, 16, v165
	v_and_b32_e32 v165, 0xffff0000, v165
	v_lshlrev_b32_e32 v166, 16, v167
	v_and_b32_e32 v167, 0xffff0000, v167
	v_pk_add_f32 v[46:47], v[46:47], v[190:191]
	v_pk_add_f32 v[48:49], v[48:49], v[164:165]
	v_pk_add_f32 v[140:141], v[44:45], v[166:167]
	v_cvt_pk_bf16_f32 v44, v46, v47
	v_cvt_pk_bf16_f32 v45, v48, v49
	v_cvt_pk_bf16_f32 v46, v138, v139
	v_cvt_pk_bf16_f32 v47, v140, v141
	v_cvt_pk_bf16_f32 v34, v26, v27
	v_cvt_pk_bf16_f32 v35, v62, v63
	v_mfma_f32_16x16x32_bf16 v[0:3], v[54:57], v[44:47], v[0:3]
	v_cvt_pk_bf16_f32 v36, v58, v59
	v_cvt_pk_bf16_f32 v37, v60, v61
	v_lshlrev_b32_e32 v168, 16, v142
	v_and_b32_e32 v169, 0xffff0000, v142
	v_mfma_f32_16x16x32_bf16 v[0:3], v[78:81], v[34:37], v[0:3]
	v_lshlrev_b32_e32 v142, 16, v143
	v_and_b32_e32 v143, 0xffff0000, v143
	v_pk_add_f32 v[70:71], v[70:71], v[168:169]
	v_pk_add_f32 v[72:73], v[72:73], v[142:143]
	v_cvt_pk_bf16_f32 v38, v64, v65
	v_cvt_pk_bf16_f32 v39, v66, v67
	v_cvt_pk_bf16_f32 v40, v70, v71
	v_cvt_pk_bf16_f32 v41, v72, v73
	v_lshlrev_b32_e32 v172, 16, v146
	v_and_b32_e32 v173, 0xffff0000, v146
	v_mfma_f32_16x16x32_bf16 v[0:3], v[82:85], v[38:41], v[0:3]
	v_lshlrev_b32_e32 v146, 16, v147
	v_and_b32_e32 v147, 0xffff0000, v147
	v_pk_add_f32 v[86:87], v[86:87], v[172:173]
	v_pk_add_f32 v[88:89], v[88:89], v[146:147]
	v_cvt_pk_bf16_f32 v42, v74, v75
	v_cvt_pk_bf16_f32 v43, v76, v77
	v_cvt_pk_bf16_f32 v44, v86, v87
	v_cvt_pk_bf16_f32 v45, v88, v89
	v_lshlrev_b32_e32 v176, 16, v150
	v_and_b32_e32 v177, 0xffff0000, v150
	v_mfma_f32_16x16x32_bf16 v[0:3], v[102:105], v[42:45], v[0:3]
	v_lshlrev_b32_e32 v150, 16, v151
	v_and_b32_e32 v151, 0xffff0000, v151
	v_pk_add_f32 v[94:95], v[94:95], v[176:177]
	v_pk_add_f32 v[96:97], v[96:97], v[150:151]
	v_cvt_pk_bf16_f32 v34, v90, v91
	v_cvt_pk_bf16_f32 v35, v92, v93
	v_cvt_pk_bf16_f32 v36, v94, v95
	v_cvt_pk_bf16_f32 v37, v96, v97
	v_lshlrev_b32_e32 v180, 16, v154
	v_and_b32_e32 v181, 0xffff0000, v154
	v_mfma_f32_16x16x32_bf16 v[0:3], v[106:109], v[34:37], v[0:3]
	v_lshlrev_b32_e32 v154, 16, v155
	v_and_b32_e32 v155, 0xffff0000, v155
	v_pk_add_f32 v[110:111], v[110:111], v[180:181]
	v_pk_add_f32 v[112:113], v[112:113], v[154:155]
	v_cvt_pk_bf16_f32 v38, v98, v99
	v_cvt_pk_bf16_f32 v39, v100, v101
	v_cvt_pk_bf16_f32 v40, v110, v111
	v_cvt_pk_bf16_f32 v41, v112, v113
	v_lshlrev_b32_e32 v184, 16, v158
	v_and_b32_e32 v185, 0xffff0000, v158
	v_mfma_f32_16x16x32_bf16 v[0:3], v[132:135], v[38:41], v[0:3]
	v_lshlrev_b32_e32 v158, 16, v159
	v_and_b32_e32 v159, 0xffff0000, v159
	v_pk_add_f32 v[118:119], v[118:119], v[184:185]
	v_pk_add_f32 v[120:121], v[120:121], v[158:159]
	v_cvt_pk_bf16_f32 v34, v114, v115
	v_cvt_pk_bf16_f32 v35, v116, v117
	v_cvt_pk_bf16_f32 v36, v118, v119
	v_cvt_pk_bf16_f32 v37, v120, v121
	s_nop 1
	v_mfma_f32_16x16x32_bf16 v[0:3], v[28:31], v[34:37], v[0:3]
	s_cbranch_scc0 .LBB0_903
	s_nop 6
	v_mul_f32_e32 v20, 0xbfb8aa3b, v0
	v_mul_f32_e32 v21, 0xbfb8aa3b, v1
	v_mul_f32_e32 v22, 0xbfb8aa3b, v2
	v_mul_f32_e32 v23, 0xbfb8aa3b, v3
	v_exp_f32_e32 v20, v20
	v_exp_f32_e32 v21, v21
	v_exp_f32_e32 v22, v22
	v_exp_f32_e32 v23, v23
	v_add_f32_e32 v20, 1.0, v20
	v_add_f32_e32 v21, 1.0, v21
	v_add_f32_e32 v22, 1.0, v22
	v_add_f32_e32 v23, 1.0, v23
	v_rcp_f32_e32 v20, v20
	v_rcp_f32_e32 v21, v21
	v_rcp_f32_e32 v22, v22
	v_rcp_f32_e32 v23, v23
	s_and_b64 s[0:1], s[20:21], exec
	s_cselect_b32 s10, s34, 0x3182000
	v_pk_mul_f32 v[0:1], v[0:1], v[20:21]
	v_pk_mul_f32 v[2:3], v[2:3], v[22:23]
	v_cvt_pk_bf16_f32 v0, v0, v1
	v_cvt_pk_bf16_f32 v1, v2, v3
	v_lshl_add_u64 v[20:21], v[6:7], 0, s[10:11]
	ds_write_b64 v32, v[0:1]
	s_waitcnt lgkmcnt(0)
	s_barrier
	global_load_dwordx4 v[0:3], v[20:21], off
	s_nop 0
	global_load_dwordx4 v[20:23], v[20:21], off offset:64
	ds_read_b128 v[24:27], v33
	ds_read_b128 v[28:31], v33 offset:64
	v_cmp_gt_i32_e32 vcc, s31, v17
	s_and_b64 s[16:17], s[16:17], vcc
	s_waitcnt vmcnt(1) lgkmcnt(1)
	v_mfma_f32_16x16x32_bf16 v[0:3], v[0:3], v[24:27], 0
	s_waitcnt vmcnt(0) lgkmcnt(0)
	v_mfma_f32_16x16x32_bf16 v[0:3], v[20:23], v[28:31], v[0:3]
	s_and_saveexec_b64 s[0:1], s[16:17]
	s_cbranch_execz .LBB0_901
	v_lshl_or_b32 v20, v15, 1, v19
	s_mov_b64 s[16:17], -1
	s_and_b64 vcc, exec, s[18:19]
	v_ashrrev_i32_e32 v19, 31, v18
	v_ashrrev_i32_e32 v21, 31, v20
	s_cbranch_vccz .LBB0_907
	v_lshlrev_b64 v[22:23], 16, v[20:21]
	v_lshl_add_u64 v[22:23], s[8:9], 0, v[22:23]
	v_lshl_add_u64 v[22:23], v[18:19], 1, v[22:23]
	v_mov_b32_e32 v15, v5
	v_lshl_add_u64 v[22:23], v[22:23], 0, v[14:15]
	v_cvt_pk_bf16_f32 v15, v1, s0
	global_store_short v[22:23], v15, off offset:1024
	v_cvt_pk_bf16_f32 v15, v2, s0
	v_cvt_pk_bf16_f32 v17, v0, s0
	global_store_short v[22:23], v15, off offset:2048
	v_cvt_pk_bf16_f32 v15, v3, s0
	global_store_short v[22:23], v17, off
	global_store_short v[22:23], v15, off offset:3072
	s_mov_b64 s[16:17], 0
